# in-proj GEMM LDS-DMA landing check strengthened: two sentinels per 128B line (one per 64B half)
# speedup vs baseline: 1.0278x; 1.0278x over previous
.LBB0_270:
	s_and_b64 s[0:1], s[20:21], exec
	s_mov_b32 s10, 208
	s_mov_b32 s11, 20648882
	s_mov_b32 s12, 6656
	s_mov_b32 s1, 2496
	s_cmov_b32 s10, 168
	s_cmov_b32 s11, 25565282
	s_cmov_b32 s12, 5376
	s_cmov_b32 s1, 2016
	v_readlane_b32 s28, v252, 0
	v_readlane_b32 s6, v252, 1
	s_lshr_b32 s6, s6, 3
	s_and_b32 s0, s28, 7
	s_mul_i32 s0, s0, s6
	s_lshr_b32 s28, s28, 3
	s_add_u32 s0, s0, s28
	s_lshl_b32 s6, s6, 3
	s_cmp_ge_u32 s0, s1
	s_cbranch_scc1 .Lgin_done
	v_and_b32_e32 v128, 31, v193
	v_lshlrev_b32_e32 v129, 7, v128
	v_bfe_u32 v130, v193, 1, 3
	v_bfe_u32 v131, v193, 5, 1
	v_xor_b32_e32 v130, v130, v131
	v_bfe_u32 v131, v193, 7, 1
	v_lshl_add_u32 v131, v131, 14, v129
	v_bfe_u32 v132, v193, 6, 1
	v_lshl_add_u32 v132, v132, 13, v129
	v_lshl_add_u32 v144, v130, 4, v131
	v_lshl_add_u32 v211, v130, 4, v132
	v_xor_b32_e32 v128, 2, v130
	v_lshl_add_u32 v146, v128, 4, v131
	v_lshl_add_u32 v248, v128, 4, v132
	v_xor_b32_e32 v128, 4, v130
	v_lshl_add_u32 v147, v128, 4, v131
	v_lshl_add_u32 v249, v128, 4, v132
	v_xor_b32_e32 v128, 6, v130
	v_lshl_add_u32 v210, v128, 4, v131
	v_lshl_add_u32 v250, v128, 4, v132
	v_and_b32_e32 v128, 7, v193
	v_bfe_u32 v129, v193, 4, 3
	v_xor_b32_e32 v128, v128, v129
	v_lshrrev_b32_e32 v129, 3, v193
	v_lshlrev_b32_e32 v129, 11, v129
	v_lshl_add_u32 v251, v128, 4, v129
	v_lshrrev_b32_e32 v128, 6, v193
	v_lshlrev_b32_e32 v128, 10, v128
	s_nop 0
	v_readfirstlane_b32 s22, v128
	v_bfe_u32 v129, v193, 3, 3
	v_lshl_add_u32 v128, v129, 12, v128
	v_and_b32_e32 v129, 7, v193
	v_lshl_add_u32 v128, v129, 7, v128
	v_lshl_add_u32 v128, v129, 2, v128
	v_bfe_u32 v129, v193, 6, 1
	v_lshl_add_u32 v145, v129, 5, v128
.Lgin_tile:
	s_mul_hi_u32 s28, s0, s11
	s_mul_i32 vcc_lo, s28, s10
	s_sub_u32 vcc_lo, s0, vcc_lo
	s_lshr_b32 vcc_hi, vcc_lo, 3
	s_and_b32 vcc_lo, vcc_lo, 7
	s_lshl_b32 s28, s28, 3
	s_add_u32 s28, s28, vcc_lo
	s_lshl_b32 s20, s28, 19
	s_add_u32 s20, s20, 29876224
	s_add_u32 s20, s94, s20
	s_addc_u32 s21, s95, 0
	s_lshl_b32 s24, vcc_hi, 18
	s_add_u32 s24, s94, s24
	s_addc_u32 s25, s95, 0
	s_mul_i32 s26, s28, s12
	s_lshl_b32 s26, s26, 8
	s_lshl_b32 vcc_hi, vcc_hi, 8
	s_add_u32 s26, s26, vcc_hi
	s_add_u32 s26, s34, s26
	s_addc_u32 s27, s35, 0
	ds_write2_b32 v145, v145, v145 offset1:16
	s_mov_b32 exec_hi, 0
	ds_write_b32 v145, v145 offset:32768
	ds_write_b32 v145, v145 offset:32832
	s_mov_b32 exec_hi, -1
	s_waitcnt lgkmcnt(0)
	s_mov_b32 m0, s22
	s_nop 0
	global_load_lds_dwordx4 v251, s[20:21]
	s_add_u32 m0, m0, 0x1000
	s_add_u32 s20, s20, 0x10000
	s_addc_u32 s21, s21, 0
	global_load_lds_dwordx4 v251, s[20:21]
	s_add_u32 m0, m0, 0x1000
	s_add_u32 s20, s20, 0x10000
	s_addc_u32 s21, s21, 0
	global_load_lds_dwordx4 v251, s[20:21]
	s_add_u32 m0, m0, 0x1000
	s_add_u32 s20, s20, 0x10000
	s_addc_u32 s21, s21, 0
	global_load_lds_dwordx4 v251, s[20:21]
	s_add_u32 m0, m0, 0x1000
	s_add_u32 s20, s20, 0x10000
	s_addc_u32 s21, s21, 0
	global_load_lds_dwordx4 v251, s[20:21]
	s_add_u32 m0, m0, 0x1000
	s_add_u32 s20, s20, 0x10000
	s_addc_u32 s21, s21, 0
	global_load_lds_dwordx4 v251, s[20:21]
	s_add_u32 m0, m0, 0x1000
	s_add_u32 s20, s20, 0x10000
	s_addc_u32 s21, s21, 0
	global_load_lds_dwordx4 v251, s[20:21]
	s_add_u32 m0, m0, 0x1000
	s_add_u32 s20, s20, 0x10000
	s_addc_u32 s21, s21, 0
	global_load_lds_dwordx4 v251, s[20:21]
	s_add_u32 m0, m0, 0x1000
	s_sub_u32 s20, s20, 458624
	s_subb_u32 s21, s21, 0
	global_load_lds_dwordx4 v251, s[24:25]
	s_add_u32 m0, m0, 0x1000
	s_add_u32 s24, s24, 0x10000
	s_addc_u32 s25, s25, 0
	global_load_lds_dwordx4 v251, s[24:25]
	s_add_u32 m0, m0, 0x1000
	s_add_u32 s24, s24, 0x10000
	s_addc_u32 s25, s25, 0
	global_load_lds_dwordx4 v251, s[24:25]
	s_add_u32 m0, m0, 0x1000
	s_add_u32 s24, s24, 0x10000
	s_addc_u32 s25, s25, 0
	global_load_lds_dwordx4 v251, s[24:25]
	s_sub_u32 s24, s24, 196480
	s_subb_u32 s25, s25, 0
	v_mov_b32_e32 v0, 0
	v_mov_b32_e32 v1, 0
	v_mov_b32_e32 v2, 0
	v_mov_b32_e32 v3, 0
	v_mov_b32_e32 v4, 0
	v_mov_b32_e32 v5, 0
	v_mov_b32_e32 v6, 0
	v_mov_b32_e32 v7, 0
	v_mov_b32_e32 v8, 0
	v_mov_b32_e32 v9, 0
	v_mov_b32_e32 v10, 0
	v_mov_b32_e32 v11, 0
	v_mov_b32_e32 v12, 0
	v_mov_b32_e32 v13, 0
	v_mov_b32_e32 v14, 0
	v_mov_b32_e32 v15, 0
	v_mov_b32_e32 v16, 0
	v_mov_b32_e32 v17, 0
	v_mov_b32_e32 v18, 0
	v_mov_b32_e32 v19, 0
	v_mov_b32_e32 v20, 0
	v_mov_b32_e32 v21, 0
	v_mov_b32_e32 v22, 0
	v_mov_b32_e32 v23, 0
	v_mov_b32_e32 v24, 0
	v_mov_b32_e32 v25, 0
	v_mov_b32_e32 v26, 0
	v_mov_b32_e32 v27, 0
	v_mov_b32_e32 v28, 0
	v_mov_b32_e32 v29, 0
	v_mov_b32_e32 v30, 0
	v_mov_b32_e32 v31, 0
	v_mov_b32_e32 v32, 0
	v_mov_b32_e32 v33, 0
	v_mov_b32_e32 v34, 0
	v_mov_b32_e32 v35, 0
	v_mov_b32_e32 v36, 0
	v_mov_b32_e32 v37, 0
	v_mov_b32_e32 v38, 0
	v_mov_b32_e32 v39, 0
	v_mov_b32_e32 v40, 0
	v_mov_b32_e32 v41, 0
	v_mov_b32_e32 v42, 0
	v_mov_b32_e32 v43, 0
	v_mov_b32_e32 v44, 0
	v_mov_b32_e32 v45, 0
	v_mov_b32_e32 v46, 0
	v_mov_b32_e32 v47, 0
	v_mov_b32_e32 v48, 0
	v_mov_b32_e32 v49, 0
	v_mov_b32_e32 v50, 0
	v_mov_b32_e32 v51, 0
	v_mov_b32_e32 v52, 0
	v_mov_b32_e32 v53, 0
	v_mov_b32_e32 v54, 0
	v_mov_b32_e32 v55, 0
	v_mov_b32_e32 v56, 0
	v_mov_b32_e32 v57, 0
	v_mov_b32_e32 v58, 0
	v_mov_b32_e32 v59, 0
	v_mov_b32_e32 v60, 0
	v_mov_b32_e32 v61, 0
	v_mov_b32_e32 v62, 0
	v_mov_b32_e32 v63, 0
	v_mov_b32_e32 v64, 0
	v_mov_b32_e32 v65, 0
	v_mov_b32_e32 v66, 0
	v_mov_b32_e32 v67, 0
	v_mov_b32_e32 v68, 0
	v_mov_b32_e32 v69, 0
	v_mov_b32_e32 v70, 0
	v_mov_b32_e32 v71, 0
	v_mov_b32_e32 v72, 0
	v_mov_b32_e32 v73, 0
	v_mov_b32_e32 v74, 0
	v_mov_b32_e32 v75, 0
	v_mov_b32_e32 v76, 0
	v_mov_b32_e32 v77, 0
	v_mov_b32_e32 v78, 0
	v_mov_b32_e32 v79, 0
	v_mov_b32_e32 v80, 0
	v_mov_b32_e32 v81, 0
	v_mov_b32_e32 v82, 0
	v_mov_b32_e32 v83, 0
	v_mov_b32_e32 v84, 0
	v_mov_b32_e32 v85, 0
	v_mov_b32_e32 v86, 0
	v_mov_b32_e32 v87, 0
	v_mov_b32_e32 v88, 0
	v_mov_b32_e32 v89, 0
	v_mov_b32_e32 v90, 0
	v_mov_b32_e32 v91, 0
	v_mov_b32_e32 v92, 0
	v_mov_b32_e32 v93, 0
	v_mov_b32_e32 v94, 0
	v_mov_b32_e32 v95, 0
	v_mov_b32_e32 v96, 0
	v_mov_b32_e32 v97, 0
	v_mov_b32_e32 v98, 0
	v_mov_b32_e32 v99, 0
	v_mov_b32_e32 v100, 0
	v_mov_b32_e32 v101, 0
	v_mov_b32_e32 v102, 0
	v_mov_b32_e32 v103, 0
	v_mov_b32_e32 v104, 0
	v_mov_b32_e32 v105, 0
	v_mov_b32_e32 v106, 0
	v_mov_b32_e32 v107, 0
	v_mov_b32_e32 v108, 0
	v_mov_b32_e32 v109, 0
	v_mov_b32_e32 v110, 0
	v_mov_b32_e32 v111, 0
	v_mov_b32_e32 v112, 0
	v_mov_b32_e32 v113, 0
	v_mov_b32_e32 v114, 0
	v_mov_b32_e32 v115, 0
	v_mov_b32_e32 v116, 0
	v_mov_b32_e32 v117, 0
	v_mov_b32_e32 v118, 0
	v_mov_b32_e32 v119, 0
	v_mov_b32_e32 v120, 0
	v_mov_b32_e32 v121, 0
	v_mov_b32_e32 v122, 0
	v_mov_b32_e32 v123, 0
	v_mov_b32_e32 v124, 0
	v_mov_b32_e32 v125, 0
	v_mov_b32_e32 v126, 0
	v_mov_b32_e32 v127, 0
	s_mov_b32 s16, 16
.Lgin_k:
	s_waitcnt vmcnt(0)
	s_barrier
	v_and_b32_e32 v128, 63, v193
	v_and_b32_e32 v129, 15, v193
	v_lshlrev_b32_e32 v128, 7, v128
	v_lshl_add_u32 v128, v129, 2, v128
	v_add_u32_e32 v129, 8192, v128
	v_add_u32_e32 v130, 16384, v128
	v_add_u32_e32 v131, 24576, v128
	v_add_u32_e32 v132, 32768, v128
	v_add_u32_e32 v133, 40960, v128
	s_mov_b32 s28, 64
.Lgin_poll:
	ds_read2_b32 v[148:149], v128 offset1:16
	ds_read2_b32 v[150:151], v129 offset1:16
	ds_read2_b32 v[152:153], v130 offset1:16
	ds_read2_b32 v[154:155], v131 offset1:16
	ds_read2_b32 v[156:157], v132 offset1:16
	ds_read2_b32 v[158:159], v133 offset1:16
	s_waitcnt lgkmcnt(5)
	v_xor_b32_e32 v148, v148, v128
	v_xor_b32_e32 v149, v149, v128
	v_min_u32_e32 v148, v148, v149
	s_waitcnt lgkmcnt(4)
	v_xor_b32_e32 v150, v150, v129
	v_xor_b32_e32 v151, v151, v129
	v_min_u32_e32 v150, v150, v151
	s_waitcnt lgkmcnt(3)
	v_xor_b32_e32 v152, v152, v130
	v_xor_b32_e32 v153, v153, v130
	v_min_u32_e32 v152, v152, v153
	s_waitcnt lgkmcnt(2)
	v_xor_b32_e32 v154, v154, v131
	v_xor_b32_e32 v155, v155, v131
	v_min_u32_e32 v154, v154, v155
	s_waitcnt lgkmcnt(1)
	v_xor_b32_e32 v156, v156, v128
	v_xor_b32_e32 v157, v157, v128
	v_min_u32_e32 v156, v156, v157
	s_waitcnt lgkmcnt(0)
	v_xor_b32_e32 v158, v158, v129
	v_xor_b32_e32 v159, v159, v129
	v_min_u32_e32 v158, v158, v159
	v_min3_u32 v148, v148, v150, v152
	v_min3_u32 v154, v154, v156, v158
	v_min_u32_e32 v148, v148, v154
	v_cmp_eq_u32_e32 vcc, 0, v148
	s_cbranch_vccz .Lgin_pollok
	s_sub_u32 s28, s28, 1
	s_cmp_lg_u32 s28, 0
	s_cbranch_scc1 .Lgin_poll
.Lgin_pollok:
	ds_read_b128 v[128:131], v144 offset:0
	ds_read_b128 v[148:151], v144 offset:4096
	ds_read_b128 v[164:167], v144 offset:8192
	ds_read_b128 v[180:183], v144 offset:12288
	ds_read_b128 v[132:135], v146 offset:0
	ds_read_b128 v[152:155], v146 offset:4096
	ds_read_b128 v[168:171], v146 offset:8192
	ds_read_b128 v[184:187], v146 offset:12288
	ds_read_b128 v[136:139], v147 offset:0
	ds_read_b128 v[156:159], v147 offset:4096
	ds_read_b128 v[172:175], v147 offset:8192
	ds_read_b128 v[188:191], v147 offset:12288
	ds_read_b128 v[140:143], v210 offset:0
	ds_read_b128 v[160:163], v210 offset:4096
	ds_read_b128 v[176:179], v210 offset:8192
	ds_read_b128 v[212:215], v210 offset:12288
	ds_read_b128 v[216:219], v211 offset:32768
	ds_read_b128 v[232:235], v211 offset:36864
	ds_read_b128 v[220:223], v248 offset:32768
	ds_read_b128 v[236:239], v248 offset:36864
	ds_read_b128 v[224:227], v249 offset:32768
	ds_read_b128 v[240:243], v249 offset:36864
	ds_read_b128 v[228:231], v250 offset:32768
	ds_read_b128 v[244:247], v250 offset:36864
	s_waitcnt lgkmcnt(0)
	s_barrier
	s_cmp_eq_u32 s16, 1
	s_cbranch_scc1 .Lgin_nodma
	ds_write2_b32 v145, v145, v145 offset1:16
	s_mov_b32 exec_hi, 0
	ds_write_b32 v145, v145 offset:32768
	ds_write_b32 v145, v145 offset:32832
	s_mov_b32 exec_hi, -1
	s_waitcnt lgkmcnt(0)
	s_mov_b32 m0, s22
	s_nop 0
	global_load_lds_dwordx4 v251, s[20:21]
	s_add_u32 m0, m0, 0x1000
	s_add_u32 s20, s20, 0x10000
	s_addc_u32 s21, s21, 0
	global_load_lds_dwordx4 v251, s[20:21]
	s_add_u32 m0, m0, 0x1000
	s_add_u32 s20, s20, 0x10000
	s_addc_u32 s21, s21, 0
	global_load_lds_dwordx4 v251, s[20:21]
	s_add_u32 m0, m0, 0x1000
	s_add_u32 s20, s20, 0x10000
	s_addc_u32 s21, s21, 0
	global_load_lds_dwordx4 v251, s[20:21]
	s_add_u32 m0, m0, 0x1000
	s_add_u32 s20, s20, 0x10000
	s_addc_u32 s21, s21, 0
	global_load_lds_dwordx4 v251, s[20:21]
	s_add_u32 m0, m0, 0x1000
	s_add_u32 s20, s20, 0x10000
	s_addc_u32 s21, s21, 0
	global_load_lds_dwordx4 v251, s[20:21]
	s_add_u32 m0, m0, 0x1000
	s_add_u32 s20, s20, 0x10000
	s_addc_u32 s21, s21, 0
	global_load_lds_dwordx4 v251, s[20:21]
	s_add_u32 m0, m0, 0x1000
	s_add_u32 s20, s20, 0x10000
	s_addc_u32 s21, s21, 0
	global_load_lds_dwordx4 v251, s[20:21]
	s_add_u32 m0, m0, 0x1000
	s_sub_u32 s20, s20, 458624
	s_subb_u32 s21, s21, 0
	global_load_lds_dwordx4 v251, s[24:25]
	s_add_u32 m0, m0, 0x1000
	s_add_u32 s24, s24, 0x10000
	s_addc_u32 s25, s25, 0
	global_load_lds_dwordx4 v251, s[24:25]
	s_add_u32 m0, m0, 0x1000
	s_add_u32 s24, s24, 0x10000
	s_addc_u32 s25, s25, 0
	global_load_lds_dwordx4 v251, s[24:25]
	s_add_u32 m0, m0, 0x1000
	s_add_u32 s24, s24, 0x10000
	s_addc_u32 s25, s25, 0
	global_load_lds_dwordx4 v251, s[24:25]
	s_sub_u32 s24, s24, 196480
	s_subb_u32 s25, s25, 0
